# speedup vs baseline: 1.0047x; 1.0004x over previous
; __global__ void __launch_bounds__(NTHR, 2) mk_fwd(Args args) {
;     ...
;             if (l == 0) {
;                 for (int idx = gtid; idx < M * 64; idx += NGT) { const int s = idx >> 6, i = idx & 63;
;                     const float inv = exp2f(-(float)i * (13.287712379549449f / 64.0f)); const float ang = (float)s * inv;
;                     const double a = (double)ang * 0.15915494309189535; const double kk = __builtin_rint(a); const float fr = (float)(a - kk);
;                     ropec[idx] = __builtin_amdgcn_cosf(fr); ropes[idx] = __builtin_amdgcn_sinf(fr); }
;             }
.LBB0_41:
	v_readlane_b32 s8, v255, 6
	v_readlane_b32 s9, v255, 7
	s_andn2_b64 vcc, exec, s[8:9]
	s_cbranch_vccnz .LBB0_50
	v_readlane_b32 s2, v253, 26
	s_nop 1
	v_add_u32_e32 v0, s2, v23
	s_mov_b32 s2, 0x100000
	v_cmp_gt_i32_e32 vcc, s2, v0
	s_and_saveexec_b64 s[8:9], vcc
	s_cbranch_execz .LBB0_45
	v_cvt_f32_ubyte0_e32 v1, v22
	v_mul_f32_e32 v2, 0xbe549a78, v1
	v_cmp_gt_f32_e32 vcc, s28, v2
	s_lshl_b32 s10, s7, 9
	v_readlane_b32 s2, v254, 61
	v_cndmask_b32_e32 v2, 0, v228, vcc
	v_fmac_f32_e32 v2, 0xbe549a78, v1
	v_exp_f32_e32 v2, v2
	s_add_u32 s0, s2, s0
	v_readlane_b32 s2, v254, 62
	v_ashrrev_i32_e32 v1, 31, v0
	v_cndmask_b32_e32 v3, 0, v227, vcc
	s_addc_u32 s1, s2, s1
	s_ashr_i32 s11, s10, 31
	v_ldexp_f32 v4, v2, v3
	v_lshl_add_u64 v[2:3], v[0:1], 2, s[0:1]
	v_mov_b32_e32 v12, s0
	v_mov_b32_e32 v13, s1
	s_lshl_b64 s[12:13], s[10:11], 2
	s_mov_b64 s[14:15], 0
.LBB0_44:
	v_and_b32_e32 v14, 0xffc03, v0
	v_and_b32_e32 v15, 0x3c0, v0
	v_lshrrev_b32_e32 v15, 4, v15
	v_or_b32_e32 v14, v14, v15
	v_and_b32_e32 v15, 24, v0
	v_lshl_or_b32 v14, v15, 3, v14
	v_and_b32_e32 v15, 4, v0
	v_lshl_or_b32 v14, v15, 6, v14
	v_and_b32_e32 v15, 32, v0
	v_lshl_or_b32 v14, v15, 4, v14
	v_mov_b32_e32 v15, v193
	v_lshl_add_u64 v[14:15], v[14:15], 2, v[12:13]
	v_add_co_u32_e32 v6, vcc, 0x400000, v14
	s_nop 1
	v_addc_co_u32_e32 v7, vcc, 0, v15, vcc
	v_ashrrev_i32_e32 v1, 6, v0
	v_cvt_f32_i32_e32 v1, v1
	v_add_u32_e32 v0, s10, v0
	s_mov_b32 s0, 0xfffff
	v_mul_f32_e32 v1, v4, v1
	v_cvt_f64_f32_e32 v[8:9], v1
	v_mul_f64 v[10:11], v[8:9], s[24:25]
	v_rndne_f64_e32 v[10:11], v[10:11]
	v_fma_f64 v[8:9], v[8:9], s[24:25], -v[10:11]
	v_cvt_f32_f64_e32 v1, v[8:9]
	v_cos_f32_e32 v5, v1
	v_sin_f32_e32 v1, v1
	v_cmp_lt_i32_e64 s[0:1], s0, v0
	s_or_b64 s[14:15], s[0:1], s[14:15]
	global_store_dword v[14:15], v5, off
	global_store_dword v[6:7], v1, off
	v_lshl_add_u64 v[2:3], v[2:3], 0, s[12:13]
	s_andn2_b64 exec, exec, s[14:15]
	s_cbranch_execnz .LBB0_44

; __device__ __forceinline__ u32x4 pack8(const f32x4 a, const f32x4 b) { u32x4 w; w.x = cvt_pk_bf16(a[0], a[1]); w.y = cvt_pk_bf16(a[2], a[3]); w.z = cvt_pk_bf16(b[0], b[1]); w.w = cvt_pk_bf16(b[2], b[3]); return w; }
;     __device__ __forceinline__ void operator()(const f32x4 (&acc)[2][2][4][2], const Unit& u, int wr, int wc, int fr_, int fq_) const {
;     ...
;             const bool isk = tile >= 16; const int t = tile - (isk ? 16 : 12), head = 2 * t + (wc >> 1), i0 = (wc & 1) * 32 + 8 * fq;
;             const float sck = isk ? 0.08838834764831845f : 1.0f; bf16_t* dst = (isk ? k : q) + head * 128 + i0;
; #pragma unroll
;             for (int ai = 0; ai < 2; ++ai)
; #pragma unroll
;                 for (int m = 0; m < 4; ++m) { const int r = row0 + ai * HALF + m * 16;
;                     const f32x4 c0 = *(const f32x4*)(rc + (unsigned)r * 64 + i0), c1 = *(const f32x4*)(rc + (unsigned)r * 64 + i0 + 4);
;                     const f32x4 s0 = *(const f32x4*)(rs + (unsigned)r * 64 + i0), s1 = *(const f32x4*)(rs + (unsigned)r * 64 + i0 + 4);
;                     const f32x4 x10 = acc[ai][0][m][0], x11 = acc[ai][0][m][1], x20 = acc[ai][1][m][0], x21 = acc[ai][1][m][1]; const float sc = sck * rv[ai][m];
;                     const f32x4 o10 = (x10 * c0 - x20 * s0) * sc, o11 = (x11 * c1 - x21 * s1) * sc;
;                     const f32x4 o20 = (x20 * c0 + x10 * s0) * sc, o21 = (x21 * c1 + x11 * s1) * sc;
;                     bf16_t* rowp = dst + (unsigned)r * 1024;
;                     *(u32x4*)rowp = pack8(o10, o11); *(u32x4*)(rowp + 64) = pack8(o20, o21); asm volatile("" ::: "memory"); }
.LBB0_135:
	s_cmp_gt_u32 s40, 11
	v_lshlrev_b32_e32 v192, 10, v149
	s_cbranch_scc0 .LBB0_137
	s_cmp_gt_u32 s40, 15
	s_cselect_b64 vcc, -1, 0
	s_cselect_b32 s2, 16, 12
	s_mov_b32 s0, 0xf300000
	s_cselect_b32 s0, s0, 0xd300000
	s_sub_i32 s2, s40, s2
	s_add_u32 s10, s5, s0
	s_addc_u32 s11, s30, 0
	s_lshl_b32 s0, s2, 8
	s_or_b32 s0, s0, s83
	v_cndmask_b32_e32 v129, 1.0, v229, vcc
	v_add_u32_e32 v134, s82, v162
	v_add_u32_e32 v131, s0, v134
	v_add_u32_e32 v131, v131, v192
	v_lshlrev_b32_e32 v132, 1, v131
	v_mov_b32_e32 v133, v193
	v_lshl_add_u64 v[132:133], v[132:133], 0, s[10:11]
	v_lshrrev_b32_e32 v131, 4, v149
	v_lshlrev_b32_e32 v131, 12, v131
	s_lshl_b32 s1, s82, 6
	v_lshl_add_u32 v131, v222, 4, v131
	v_add_u32_e32 v131, s1, v131
	global_load_dwordx4 v[164:167], v131, s[44:45] offset:1024
	global_load_dwordx4 v[168:171], v131, s[44:45]
	global_load_dwordx4 v[172:175], v131, s[46:47] offset:1024
	global_load_dwordx4 v[180:183], v131, s[46:47]
	v_add_u32_e32 v131, 0x1000, v131
	global_load_dwordx4 v[184:187], v131, s[44:45] offset:1024
	global_load_dwordx4 v[188:191], v131, s[44:45]
	global_load_dwordx4 v[206:209], v131, s[46:47] offset:1024
	global_load_dwordx4 v[210:213], v131, s[46:47]
	v_mul_f32_e32 v232, v129, v160
	s_waitcnt vmcnt(4)
	v_pk_mul_f32 v[214:215], v[118:119], v[182:183]
	v_pk_mul_f32 v[216:217], v[116:117], v[180:181]
	v_pk_mul_f32 v[218:219], v[114:115], v[174:175]
	v_pk_mul_f32 v[220:221], v[112:113], v[172:173]
	v_pk_mul_f32 v[194:195], v[126:127], v[182:183]
	v_pk_mul_f32 v[196:197], v[124:125], v[180:181]
	v_pk_mul_f32 v[202:203], v[122:123], v[174:175]
	v_pk_mul_f32 v[204:205], v[120:121], v[172:173]
	v_pk_fma_f32 v[214:215], v[126:127], v[170:171], v[214:215] neg_lo:[0,0,1] neg_hi:[0,0,1]
	v_pk_fma_f32 v[216:217], v[124:125], v[168:169], v[216:217] neg_lo:[0,0,1] neg_hi:[0,0,1]
	v_pk_fma_f32 v[218:219], v[122:123], v[166:167], v[218:219] neg_lo:[0,0,1] neg_hi:[0,0,1]
	v_pk_fma_f32 v[220:221], v[120:121], v[164:165], v[220:221] neg_lo:[0,0,1] neg_hi:[0,0,1]
	v_pk_fma_f32 v[194:195], v[118:119], v[170:171], v[194:195]
	v_pk_fma_f32 v[196:197], v[116:117], v[168:169], v[196:197]
	v_pk_fma_f32 v[202:203], v[114:115], v[166:167], v[202:203]
	v_pk_fma_f32 v[204:205], v[112:113], v[164:165], v[204:205]
	v_pk_mul_f32 v[214:215], v[232:233], v[214:215] op_sel_hi:[0,1]
	v_pk_mul_f32 v[216:217], v[232:233], v[216:217] op_sel_hi:[0,1]
	v_pk_mul_f32 v[218:219], v[232:233], v[218:219] op_sel_hi:[0,1]
	v_pk_mul_f32 v[220:221], v[232:233], v[220:221] op_sel_hi:[0,1]
	v_pk_mul_f32 v[194:195], v[232:233], v[194:195] op_sel_hi:[0,1]
	v_pk_mul_f32 v[196:197], v[232:233], v[196:197] op_sel_hi:[0,1]
	v_pk_mul_f32 v[202:203], v[232:233], v[202:203] op_sel_hi:[0,1]
	v_pk_mul_f32 v[204:205], v[232:233], v[204:205] op_sel_hi:[0,1]
	v_cvt_pk_bf16_f32 v124, v216, v217
	v_cvt_pk_bf16_f32 v125, v214, v215
	v_cvt_pk_bf16_f32 v126, v220, v221
	v_cvt_pk_bf16_f32 v127, v218, v219
	v_cvt_pk_bf16_f32 v120, v196, v197
	v_cvt_pk_bf16_f32 v121, v194, v195
	v_cvt_pk_bf16_f32 v122, v204, v205
	v_cvt_pk_bf16_f32 v123, v202, v203
	global_store_dwordx4 v[132:133], v[124:127], off
	global_store_dwordx4 v[132:133], v[120:123], off offset:128
	s_mov_b32 s0, 0x8000
	s_mov_b32 s1, 0
	v_lshl_add_u64 v[132:133], v[132:133], 0, s[0:1]
	v_add_u32_e32 v131, 0x1000, v131
	global_load_dwordx4 v[164:167], v131, s[44:45] offset:1024
	global_load_dwordx4 v[168:171], v131, s[44:45]
	global_load_dwordx4 v[172:175], v131, s[46:47] offset:1024
	global_load_dwordx4 v[180:183], v131, s[46:47]
	v_mul_f32_e32 v232, v129, v158
	s_waitcnt vmcnt(6)
	v_pk_mul_f32 v[214:215], v[102:103], v[212:213]
	v_pk_mul_f32 v[216:217], v[100:101], v[210:211]
	v_pk_mul_f32 v[218:219], v[98:99], v[208:209]
	v_pk_mul_f32 v[220:221], v[96:97], v[206:207]
	v_pk_mul_f32 v[194:195], v[110:111], v[212:213]
	v_pk_mul_f32 v[196:197], v[108:109], v[210:211]
	v_pk_mul_f32 v[202:203], v[106:107], v[208:209]
	v_pk_mul_f32 v[204:205], v[104:105], v[206:207]
	v_pk_fma_f32 v[214:215], v[110:111], v[190:191], v[214:215] neg_lo:[0,0,1] neg_hi:[0,0,1]
	v_pk_fma_f32 v[216:217], v[108:109], v[188:189], v[216:217] neg_lo:[0,0,1] neg_hi:[0,0,1]
	v_pk_fma_f32 v[218:219], v[106:107], v[186:187], v[218:219] neg_lo:[0,0,1] neg_hi:[0,0,1]
	v_pk_fma_f32 v[220:221], v[104:105], v[184:185], v[220:221] neg_lo:[0,0,1] neg_hi:[0,0,1]
	v_pk_fma_f32 v[194:195], v[102:103], v[190:191], v[194:195]
	v_pk_fma_f32 v[196:197], v[100:101], v[188:189], v[196:197]
	v_pk_fma_f32 v[202:203], v[98:99], v[186:187], v[202:203]
	v_pk_fma_f32 v[204:205], v[96:97], v[184:185], v[204:205]
	v_pk_mul_f32 v[214:215], v[232:233], v[214:215] op_sel_hi:[0,1]
	v_pk_mul_f32 v[216:217], v[232:233], v[216:217] op_sel_hi:[0,1]
	v_pk_mul_f32 v[218:219], v[232:233], v[218:219] op_sel_hi:[0,1]
	v_pk_mul_f32 v[220:221], v[232:233], v[220:221] op_sel_hi:[0,1]
	v_pk_mul_f32 v[194:195], v[232:233], v[194:195] op_sel_hi:[0,1]
	v_pk_mul_f32 v[196:197], v[232:233], v[196:197] op_sel_hi:[0,1]
	v_pk_mul_f32 v[202:203], v[232:233], v[202:203] op_sel_hi:[0,1]
	v_pk_mul_f32 v[204:205], v[232:233], v[204:205] op_sel_hi:[0,1]
	v_cvt_pk_bf16_f32 v108, v216, v217
	v_cvt_pk_bf16_f32 v109, v214, v215
	v_cvt_pk_bf16_f32 v110, v220, v221
	v_cvt_pk_bf16_f32 v111, v218, v219
	v_cvt_pk_bf16_f32 v104, v196, v197
	v_cvt_pk_bf16_f32 v105, v194, v195
	v_cvt_pk_bf16_f32 v106, v204, v205
	v_cvt_pk_bf16_f32 v107, v202, v203
	global_store_dwordx4 v[132:133], v[108:111], off
	global_store_dwordx4 v[132:133], v[104:107], off offset:128
	s_mov_b32 s0, 0x8000
	s_mov_b32 s1, 0
	v_lshl_add_u64 v[132:133], v[132:133], 0, s[0:1]
	v_add_u32_e32 v131, 0x1000, v131
	global_load_dwordx4 v[184:187], v131, s[44:45] offset:1024
	global_load_dwordx4 v[188:191], v131, s[44:45]
	global_load_dwordx4 v[206:209], v131, s[46:47] offset:1024
	global_load_dwordx4 v[210:213], v131, s[46:47]
	v_mul_f32_e32 v232, v129, v156
	s_waitcnt vmcnt(6)
; __device__ __forceinline__ u32x4 pack8(const f32x4 a, const f32x4 b) { u32x4 w; w.x = cvt_pk_bf16(a[0], a[1]); w.y = cvt_pk_bf16(a[2], a[3]); w.z = cvt_pk_bf16(b[0], b[1]); w.w = cvt_pk_bf16(b[2], b[3]); return w; }
;     __device__ __forceinline__ void operator()(const f32x4 (&acc)[2][2][4][2], const Unit& u, int wr, int wc, int fr_, int fq_) const {
;     ...
;                 for (int m = 0; m < 4; ++m) { const int r = row0 + ai * HALF + m * 16;
;                     const f32x4 c0 = *(const f32x4*)(rc + (unsigned)r * 64 + i0), c1 = *(const f32x4*)(rc + (unsigned)r * 64 + i0 + 4);
;                     const f32x4 s0 = *(const f32x4*)(rs + (unsigned)r * 64 + i0), s1 = *(const f32x4*)(rs + (unsigned)r * 64 + i0 + 4);
;                     const f32x4 x10 = acc[ai][0][m][0], x11 = acc[ai][0][m][1], x20 = acc[ai][1][m][0], x21 = acc[ai][1][m][1]; const float sc = sck * rv[ai][m];
;                     const f32x4 o10 = (x10 * c0 - x20 * s0) * sc, o11 = (x11 * c1 - x21 * s1) * sc;
;                     const f32x4 o20 = (x20 * c0 + x10 * s0) * sc, o21 = (x21 * c1 + x11 * s1) * sc;
;                     bf16_t* rowp = dst + (unsigned)r * 1024;
;                     *(u32x4*)rowp = pack8(o10, o11); *(u32x4*)(rowp + 64) = pack8(o20, o21); asm volatile("" ::: "memory"); }
	v_pk_mul_f32 v[214:215], v[86:87], v[182:183]
	v_pk_mul_f32 v[216:217], v[84:85], v[180:181]
	v_pk_mul_f32 v[218:219], v[82:83], v[174:175]
	v_pk_mul_f32 v[220:221], v[80:81], v[172:173]
	v_pk_mul_f32 v[194:195], v[94:95], v[182:183]
	v_pk_mul_f32 v[196:197], v[92:93], v[180:181]
	v_pk_mul_f32 v[202:203], v[90:91], v[174:175]
	v_pk_mul_f32 v[204:205], v[88:89], v[172:173]
	v_pk_fma_f32 v[214:215], v[94:95], v[170:171], v[214:215] neg_lo:[0,0,1] neg_hi:[0,0,1]
	v_pk_fma_f32 v[216:217], v[92:93], v[168:169], v[216:217] neg_lo:[0,0,1] neg_hi:[0,0,1]
	v_pk_fma_f32 v[218:219], v[90:91], v[166:167], v[218:219] neg_lo:[0,0,1] neg_hi:[0,0,1]
	v_pk_fma_f32 v[220:221], v[88:89], v[164:165], v[220:221] neg_lo:[0,0,1] neg_hi:[0,0,1]
	v_pk_fma_f32 v[194:195], v[86:87], v[170:171], v[194:195]
	v_pk_fma_f32 v[196:197], v[84:85], v[168:169], v[196:197]
	v_pk_fma_f32 v[202:203], v[82:83], v[166:167], v[202:203]
	v_pk_fma_f32 v[204:205], v[80:81], v[164:165], v[204:205]
	v_pk_mul_f32 v[214:215], v[232:233], v[214:215] op_sel_hi:[0,1]
	v_pk_mul_f32 v[216:217], v[232:233], v[216:217] op_sel_hi:[0,1]
	v_pk_mul_f32 v[218:219], v[232:233], v[218:219] op_sel_hi:[0,1]
	v_pk_mul_f32 v[220:221], v[232:233], v[220:221] op_sel_hi:[0,1]
	v_pk_mul_f32 v[194:195], v[232:233], v[194:195] op_sel_hi:[0,1]
	v_pk_mul_f32 v[196:197], v[232:233], v[196:197] op_sel_hi:[0,1]
	v_pk_mul_f32 v[202:203], v[232:233], v[202:203] op_sel_hi:[0,1]
	v_pk_mul_f32 v[204:205], v[232:233], v[204:205] op_sel_hi:[0,1]
	v_cvt_pk_bf16_f32 v92, v216, v217
	v_cvt_pk_bf16_f32 v93, v214, v215
	v_cvt_pk_bf16_f32 v94, v220, v221
	v_cvt_pk_bf16_f32 v95, v218, v219
	v_cvt_pk_bf16_f32 v88, v196, v197
	v_cvt_pk_bf16_f32 v89, v194, v195
	v_cvt_pk_bf16_f32 v90, v204, v205
	v_cvt_pk_bf16_f32 v91, v202, v203
	global_store_dwordx4 v[132:133], v[92:95], off
	global_store_dwordx4 v[132:133], v[88:91], off offset:128
	s_mov_b32 s0, 0x8000
	s_mov_b32 s1, 0
	v_lshl_add_u64 v[132:133], v[132:133], 0, s[0:1]
	v_add_u32_e32 v131, 0x5000, v131
	global_load_dwordx4 v[164:167], v131, s[44:45] offset:1024
	global_load_dwordx4 v[168:171], v131, s[44:45]
	global_load_dwordx4 v[172:175], v131, s[46:47] offset:1024
	global_load_dwordx4 v[180:183], v131, s[46:47]
	v_mul_f32_e32 v232, v129, v154
	s_waitcnt vmcnt(6)
	v_pk_mul_f32 v[214:215], v[70:71], v[212:213]
	v_pk_mul_f32 v[216:217], v[68:69], v[210:211]
	v_pk_mul_f32 v[218:219], v[66:67], v[208:209]
	v_pk_mul_f32 v[220:221], v[64:65], v[206:207]
	v_pk_mul_f32 v[194:195], v[78:79], v[212:213]
	v_pk_mul_f32 v[196:197], v[76:77], v[210:211]
	v_pk_mul_f32 v[202:203], v[74:75], v[208:209]
	v_pk_mul_f32 v[204:205], v[72:73], v[206:207]
	v_pk_fma_f32 v[214:215], v[78:79], v[190:191], v[214:215] neg_lo:[0,0,1] neg_hi:[0,0,1]
	v_pk_fma_f32 v[216:217], v[76:77], v[188:189], v[216:217] neg_lo:[0,0,1] neg_hi:[0,0,1]
	v_pk_fma_f32 v[218:219], v[74:75], v[186:187], v[218:219] neg_lo:[0,0,1] neg_hi:[0,0,1]
	v_pk_fma_f32 v[220:221], v[72:73], v[184:185], v[220:221] neg_lo:[0,0,1] neg_hi:[0,0,1]
	v_pk_fma_f32 v[194:195], v[70:71], v[190:191], v[194:195]
	v_pk_fma_f32 v[196:197], v[68:69], v[188:189], v[196:197]
	v_pk_fma_f32 v[202:203], v[66:67], v[186:187], v[202:203]
	v_pk_fma_f32 v[204:205], v[64:65], v[184:185], v[204:205]
	v_pk_mul_f32 v[214:215], v[232:233], v[214:215] op_sel_hi:[0,1]
	v_pk_mul_f32 v[216:217], v[232:233], v[216:217] op_sel_hi:[0,1]
	v_pk_mul_f32 v[218:219], v[232:233], v[218:219] op_sel_hi:[0,1]
	v_pk_mul_f32 v[220:221], v[232:233], v[220:221] op_sel_hi:[0,1]
	v_pk_mul_f32 v[194:195], v[232:233], v[194:195] op_sel_hi:[0,1]
	v_pk_mul_f32 v[196:197], v[232:233], v[196:197] op_sel_hi:[0,1]
	v_pk_mul_f32 v[202:203], v[232:233], v[202:203] op_sel_hi:[0,1]
	v_pk_mul_f32 v[204:205], v[232:233], v[204:205] op_sel_hi:[0,1]
	v_cvt_pk_bf16_f32 v76, v216, v217
	v_cvt_pk_bf16_f32 v77, v214, v215
	v_cvt_pk_bf16_f32 v78, v220, v221
	v_cvt_pk_bf16_f32 v79, v218, v219
	v_cvt_pk_bf16_f32 v72, v196, v197
	v_cvt_pk_bf16_f32 v73, v194, v195
	v_cvt_pk_bf16_f32 v74, v204, v205
	v_cvt_pk_bf16_f32 v75, v202, v203
	global_store_dwordx4 v[132:133], v[76:79], off
	global_store_dwordx4 v[132:133], v[72:75], off offset:128
	s_mov_b32 s0, 0x28000
	s_mov_b32 s1, 0
	v_lshl_add_u64 v[132:133], v[132:133], 0, s[0:1]
	v_add_u32_e32 v131, 0x1000, v131
	global_load_dwordx4 v[184:187], v131, s[44:45] offset:1024
	global_load_dwordx4 v[188:191], v131, s[44:45]
	global_load_dwordx4 v[206:209], v131, s[46:47] offset:1024
	global_load_dwordx4 v[210:213], v131, s[46:47]
	v_mul_f32_e32 v232, v129, v152
	s_waitcnt vmcnt(6)
; __device__ __forceinline__ u32x4 pack8(const f32x4 a, const f32x4 b) { u32x4 w; w.x = cvt_pk_bf16(a[0], a[1]); w.y = cvt_pk_bf16(a[2], a[3]); w.z = cvt_pk_bf16(b[0], b[1]); w.w = cvt_pk_bf16(b[2], b[3]); return w; }
;     __device__ __forceinline__ void operator()(const f32x4 (&acc)[2][2][4][2], const Unit& u, int wr, int wc, int fr_, int fq_) const {
;     ...
;                 for (int m = 0; m < 4; ++m) { const int r = row0 + ai * HALF + m * 16;
;                     const f32x4 c0 = *(const f32x4*)(rc + (unsigned)r * 64 + i0), c1 = *(const f32x4*)(rc + (unsigned)r * 64 + i0 + 4);
;                     const f32x4 s0 = *(const f32x4*)(rs + (unsigned)r * 64 + i0), s1 = *(const f32x4*)(rs + (unsigned)r * 64 + i0 + 4);
;                     const f32x4 x10 = acc[ai][0][m][0], x11 = acc[ai][0][m][1], x20 = acc[ai][1][m][0], x21 = acc[ai][1][m][1]; const float sc = sck * rv[ai][m];
;                     const f32x4 o10 = (x10 * c0 - x20 * s0) * sc, o11 = (x11 * c1 - x21 * s1) * sc;
;                     const f32x4 o20 = (x20 * c0 + x10 * s0) * sc, o21 = (x21 * c1 + x11 * s1) * sc;
;                     bf16_t* rowp = dst + (unsigned)r * 1024;
;                     *(u32x4*)rowp = pack8(o10, o11); *(u32x4*)(rowp + 64) = pack8(o20, o21); asm volatile("" ::: "memory"); }
	v_pk_mul_f32 v[214:215], v[54:55], v[182:183]
	v_pk_mul_f32 v[216:217], v[52:53], v[180:181]
	v_pk_mul_f32 v[218:219], v[50:51], v[174:175]
	v_pk_mul_f32 v[220:221], v[48:49], v[172:173]
	v_pk_mul_f32 v[194:195], v[62:63], v[182:183]
	v_pk_mul_f32 v[196:197], v[60:61], v[180:181]
	v_pk_mul_f32 v[202:203], v[58:59], v[174:175]
	v_pk_mul_f32 v[204:205], v[56:57], v[172:173]
	v_pk_fma_f32 v[214:215], v[62:63], v[170:171], v[214:215] neg_lo:[0,0,1] neg_hi:[0,0,1]
	v_pk_fma_f32 v[216:217], v[60:61], v[168:169], v[216:217] neg_lo:[0,0,1] neg_hi:[0,0,1]
	v_pk_fma_f32 v[218:219], v[58:59], v[166:167], v[218:219] neg_lo:[0,0,1] neg_hi:[0,0,1]
	v_pk_fma_f32 v[220:221], v[56:57], v[164:165], v[220:221] neg_lo:[0,0,1] neg_hi:[0,0,1]
	v_pk_fma_f32 v[194:195], v[54:55], v[170:171], v[194:195]
	v_pk_fma_f32 v[196:197], v[52:53], v[168:169], v[196:197]
	v_pk_fma_f32 v[202:203], v[50:51], v[166:167], v[202:203]
	v_pk_fma_f32 v[204:205], v[48:49], v[164:165], v[204:205]
	v_pk_mul_f32 v[214:215], v[232:233], v[214:215] op_sel_hi:[0,1]
	v_pk_mul_f32 v[216:217], v[232:233], v[216:217] op_sel_hi:[0,1]
	v_pk_mul_f32 v[218:219], v[232:233], v[218:219] op_sel_hi:[0,1]
	v_pk_mul_f32 v[220:221], v[232:233], v[220:221] op_sel_hi:[0,1]
	v_pk_mul_f32 v[194:195], v[232:233], v[194:195] op_sel_hi:[0,1]
	v_pk_mul_f32 v[196:197], v[232:233], v[196:197] op_sel_hi:[0,1]
	v_pk_mul_f32 v[202:203], v[232:233], v[202:203] op_sel_hi:[0,1]
	v_pk_mul_f32 v[204:205], v[232:233], v[204:205] op_sel_hi:[0,1]
	v_cvt_pk_bf16_f32 v60, v216, v217
	v_cvt_pk_bf16_f32 v61, v214, v215
	v_cvt_pk_bf16_f32 v62, v220, v221
	v_cvt_pk_bf16_f32 v63, v218, v219
	v_cvt_pk_bf16_f32 v56, v196, v197
	v_cvt_pk_bf16_f32 v57, v194, v195
	v_cvt_pk_bf16_f32 v58, v204, v205
	v_cvt_pk_bf16_f32 v59, v202, v203
	global_store_dwordx4 v[132:133], v[60:63], off
	global_store_dwordx4 v[132:133], v[56:59], off offset:128
	s_mov_b32 s0, 0x8000
	s_mov_b32 s1, 0
	v_lshl_add_u64 v[132:133], v[132:133], 0, s[0:1]
	v_add_u32_e32 v131, 0x1000, v131
	global_load_dwordx4 v[164:167], v131, s[44:45] offset:1024
	global_load_dwordx4 v[168:171], v131, s[44:45]
	global_load_dwordx4 v[172:175], v131, s[46:47] offset:1024
	global_load_dwordx4 v[180:183], v131, s[46:47]
	v_mul_f32_e32 v232, v129, v150
	s_waitcnt vmcnt(6)
	v_pk_mul_f32 v[214:215], v[38:39], v[212:213]
	v_pk_mul_f32 v[216:217], v[36:37], v[210:211]
	v_pk_mul_f32 v[218:219], v[34:35], v[208:209]
	v_pk_mul_f32 v[220:221], v[32:33], v[206:207]
	v_pk_mul_f32 v[194:195], v[46:47], v[212:213]
	v_pk_mul_f32 v[196:197], v[44:45], v[210:211]
	v_pk_mul_f32 v[202:203], v[42:43], v[208:209]
	v_pk_mul_f32 v[204:205], v[40:41], v[206:207]
	v_pk_fma_f32 v[214:215], v[46:47], v[190:191], v[214:215] neg_lo:[0,0,1] neg_hi:[0,0,1]
	v_pk_fma_f32 v[216:217], v[44:45], v[188:189], v[216:217] neg_lo:[0,0,1] neg_hi:[0,0,1]
	v_pk_fma_f32 v[218:219], v[42:43], v[186:187], v[218:219] neg_lo:[0,0,1] neg_hi:[0,0,1]
	v_pk_fma_f32 v[220:221], v[40:41], v[184:185], v[220:221] neg_lo:[0,0,1] neg_hi:[0,0,1]
	v_pk_fma_f32 v[194:195], v[38:39], v[190:191], v[194:195]
	v_pk_fma_f32 v[196:197], v[36:37], v[188:189], v[196:197]
	v_pk_fma_f32 v[202:203], v[34:35], v[186:187], v[202:203]
	v_pk_fma_f32 v[204:205], v[32:33], v[184:185], v[204:205]
	v_pk_mul_f32 v[214:215], v[232:233], v[214:215] op_sel_hi:[0,1]
	v_pk_mul_f32 v[216:217], v[232:233], v[216:217] op_sel_hi:[0,1]
	v_pk_mul_f32 v[218:219], v[232:233], v[218:219] op_sel_hi:[0,1]
	v_pk_mul_f32 v[220:221], v[232:233], v[220:221] op_sel_hi:[0,1]
	v_pk_mul_f32 v[194:195], v[232:233], v[194:195] op_sel_hi:[0,1]
	v_pk_mul_f32 v[196:197], v[232:233], v[196:197] op_sel_hi:[0,1]
	v_pk_mul_f32 v[202:203], v[232:233], v[202:203] op_sel_hi:[0,1]
	v_pk_mul_f32 v[204:205], v[232:233], v[204:205] op_sel_hi:[0,1]
	v_cvt_pk_bf16_f32 v44, v216, v217
	v_cvt_pk_bf16_f32 v45, v214, v215
	v_cvt_pk_bf16_f32 v46, v220, v221
	v_cvt_pk_bf16_f32 v47, v218, v219
	v_cvt_pk_bf16_f32 v40, v196, v197
	v_cvt_pk_bf16_f32 v41, v194, v195
	v_cvt_pk_bf16_f32 v42, v204, v205
	v_cvt_pk_bf16_f32 v43, v202, v203
	global_store_dwordx4 v[132:133], v[44:47], off
	global_store_dwordx4 v[132:133], v[40:43], off offset:128
	s_mov_b32 s0, 0x8000
	s_mov_b32 s1, 0
	v_lshl_add_u64 v[132:133], v[132:133], 0, s[0:1]
	v_add_u32_e32 v131, 0x1000, v131
	global_load_dwordx4 v[184:187], v131, s[44:45] offset:1024
	global_load_dwordx4 v[188:191], v131, s[44:45]
	global_load_dwordx4 v[206:209], v131, s[46:47] offset:1024
	global_load_dwordx4 v[210:213], v131, s[46:47]
	v_mul_f32_e32 v232, v129, v148
	s_waitcnt vmcnt(6)
; __device__ __forceinline__ u32x4 pack8(const f32x4 a, const f32x4 b) { u32x4 w; w.x = cvt_pk_bf16(a[0], a[1]); w.y = cvt_pk_bf16(a[2], a[3]); w.z = cvt_pk_bf16(b[0], b[1]); w.w = cvt_pk_bf16(b[2], b[3]); return w; }
;     __device__ __forceinline__ void operator()(const f32x4 (&acc)[2][2][4][2], const Unit& u, int wr, int wc, int fr_, int fq_) const {
;     ...
;                 for (int m = 0; m < 4; ++m) { const int r = row0 + ai * HALF + m * 16;
;                     const f32x4 c0 = *(const f32x4*)(rc + (unsigned)r * 64 + i0), c1 = *(const f32x4*)(rc + (unsigned)r * 64 + i0 + 4);
;                     const f32x4 s0 = *(const f32x4*)(rs + (unsigned)r * 64 + i0), s1 = *(const f32x4*)(rs + (unsigned)r * 64 + i0 + 4);
;                     const f32x4 x10 = acc[ai][0][m][0], x11 = acc[ai][0][m][1], x20 = acc[ai][1][m][0], x21 = acc[ai][1][m][1]; const float sc = sck * rv[ai][m];
;                     const f32x4 o10 = (x10 * c0 - x20 * s0) * sc, o11 = (x11 * c1 - x21 * s1) * sc;
;                     const f32x4 o20 = (x20 * c0 + x10 * s0) * sc, o21 = (x21 * c1 + x11 * s1) * sc;
;                     bf16_t* rowp = dst + (unsigned)r * 1024;
;                     *(u32x4*)rowp = pack8(o10, o11); *(u32x4*)(rowp + 64) = pack8(o20, o21); asm volatile("" ::: "memory"); }
	v_pk_mul_f32 v[214:215], v[22:23], v[182:183]
	v_pk_mul_f32 v[216:217], v[20:21], v[180:181]
	v_pk_mul_f32 v[218:219], v[18:19], v[174:175]
	v_pk_mul_f32 v[220:221], v[16:17], v[172:173]
	v_pk_mul_f32 v[194:195], v[30:31], v[182:183]
	v_pk_mul_f32 v[196:197], v[28:29], v[180:181]
	v_pk_mul_f32 v[202:203], v[26:27], v[174:175]
	v_pk_mul_f32 v[204:205], v[24:25], v[172:173]
	v_pk_fma_f32 v[214:215], v[30:31], v[170:171], v[214:215] neg_lo:[0,0,1] neg_hi:[0,0,1]
	v_pk_fma_f32 v[216:217], v[28:29], v[168:169], v[216:217] neg_lo:[0,0,1] neg_hi:[0,0,1]
	v_pk_fma_f32 v[218:219], v[26:27], v[166:167], v[218:219] neg_lo:[0,0,1] neg_hi:[0,0,1]
	v_pk_fma_f32 v[220:221], v[24:25], v[164:165], v[220:221] neg_lo:[0,0,1] neg_hi:[0,0,1]
	v_pk_fma_f32 v[194:195], v[22:23], v[170:171], v[194:195]
	v_pk_fma_f32 v[196:197], v[20:21], v[168:169], v[196:197]
	v_pk_fma_f32 v[202:203], v[18:19], v[166:167], v[202:203]
	v_pk_fma_f32 v[204:205], v[16:17], v[164:165], v[204:205]
	v_pk_mul_f32 v[214:215], v[232:233], v[214:215] op_sel_hi:[0,1]
	v_pk_mul_f32 v[216:217], v[232:233], v[216:217] op_sel_hi:[0,1]
	v_pk_mul_f32 v[218:219], v[232:233], v[218:219] op_sel_hi:[0,1]
	v_pk_mul_f32 v[220:221], v[232:233], v[220:221] op_sel_hi:[0,1]
	v_pk_mul_f32 v[194:195], v[232:233], v[194:195] op_sel_hi:[0,1]
	v_pk_mul_f32 v[196:197], v[232:233], v[196:197] op_sel_hi:[0,1]
	v_pk_mul_f32 v[202:203], v[232:233], v[202:203] op_sel_hi:[0,1]
	v_pk_mul_f32 v[204:205], v[232:233], v[204:205] op_sel_hi:[0,1]
	v_cvt_pk_bf16_f32 v28, v216, v217
	v_cvt_pk_bf16_f32 v29, v214, v215
	v_cvt_pk_bf16_f32 v30, v220, v221
	v_cvt_pk_bf16_f32 v31, v218, v219
	v_cvt_pk_bf16_f32 v24, v196, v197
	v_cvt_pk_bf16_f32 v25, v194, v195
	v_cvt_pk_bf16_f32 v26, v204, v205
	v_cvt_pk_bf16_f32 v27, v202, v203
	global_store_dwordx4 v[132:133], v[28:31], off
	global_store_dwordx4 v[132:133], v[24:27], off offset:128
	s_mov_b32 s0, 0x8000
	s_mov_b32 s1, 0
	v_lshl_add_u64 v[132:133], v[132:133], 0, s[0:1]
	v_mul_f32_e32 v232, v129, v128
	s_waitcnt vmcnt(2)
	v_pk_mul_f32 v[214:215], v[6:7], v[212:213]
	v_pk_mul_f32 v[216:217], v[4:5], v[210:211]
	v_pk_mul_f32 v[218:219], v[2:3], v[208:209]
	v_pk_mul_f32 v[220:221], v[0:1], v[206:207]
	v_pk_mul_f32 v[194:195], v[14:15], v[212:213]
	v_pk_mul_f32 v[196:197], v[12:13], v[210:211]
	v_pk_mul_f32 v[202:203], v[10:11], v[208:209]
	v_pk_mul_f32 v[204:205], v[8:9], v[206:207]
	v_pk_fma_f32 v[214:215], v[14:15], v[190:191], v[214:215] neg_lo:[0,0,1] neg_hi:[0,0,1]
	v_pk_fma_f32 v[216:217], v[12:13], v[188:189], v[216:217] neg_lo:[0,0,1] neg_hi:[0,0,1]
	v_pk_fma_f32 v[218:219], v[10:11], v[186:187], v[218:219] neg_lo:[0,0,1] neg_hi:[0,0,1]
	v_pk_fma_f32 v[220:221], v[8:9], v[184:185], v[220:221] neg_lo:[0,0,1] neg_hi:[0,0,1]
	v_pk_fma_f32 v[194:195], v[6:7], v[190:191], v[194:195]
	v_pk_fma_f32 v[196:197], v[4:5], v[188:189], v[196:197]
	v_pk_fma_f32 v[202:203], v[2:3], v[186:187], v[202:203]
	v_pk_fma_f32 v[204:205], v[0:1], v[184:185], v[204:205]
	v_pk_mul_f32 v[214:215], v[232:233], v[214:215] op_sel_hi:[0,1]
	v_pk_mul_f32 v[216:217], v[232:233], v[216:217] op_sel_hi:[0,1]
	v_pk_mul_f32 v[218:219], v[232:233], v[218:219] op_sel_hi:[0,1]
	v_pk_mul_f32 v[220:221], v[232:233], v[220:221] op_sel_hi:[0,1]
	v_pk_mul_f32 v[194:195], v[232:233], v[194:195] op_sel_hi:[0,1]
	v_pk_mul_f32 v[196:197], v[232:233], v[196:197] op_sel_hi:[0,1]
	v_pk_mul_f32 v[202:203], v[232:233], v[202:203] op_sel_hi:[0,1]
	v_pk_mul_f32 v[204:205], v[232:233], v[204:205] op_sel_hi:[0,1]
	v_cvt_pk_bf16_f32 v12, v216, v217
	v_cvt_pk_bf16_f32 v13, v214, v215
	v_cvt_pk_bf16_f32 v14, v220, v221
	v_cvt_pk_bf16_f32 v15, v218, v219
	v_cvt_pk_bf16_f32 v8, v196, v197
	v_cvt_pk_bf16_f32 v9, v194, v195
	v_cvt_pk_bf16_f32 v10, v204, v205
	v_cvt_pk_bf16_f32 v11, v202, v203
	global_store_dwordx4 v[132:133], v[12:15], off
	global_store_dwordx4 v[132:133], v[8:11], off offset:128
	s_branch .LBB0_134
